# INPROJ K-loop: LDS-DMA loads addressed by scalar base + 32-bit lane offset as well
# baseline (speedup 1.0000x reference)
; #define PG8_STAGE(bufoff, gbase, voff) do { _Pragma("unroll") for (int _i = 0; _i < 2; ++_i) \
;         __builtin_amdgcn_global_load_lds((const unsigned*)((const char*)(gbase) + (voff)[_i]), (PG8_LAS unsigned*)(lds + (bufoff) + ldsw + _i * 8192), 16, 0, 0); } while (0)
; #define PG8_LDA(dst, b, h) do { _Pragma("unroll") for (int m = 0; m < 4; ++m) _Pragma("unroll") for (int k = 0; k < 2; ++k) dst[m][k] = *(const PG8_LAS bf16x8*)(lds + PG8_SA(b, h) + aoff + m * 2048 + k * 1024); } while (0)
; #define PG8_LDB(dst, b, h) do { _Pragma("unroll") for (int n = 0; n < 2; ++n) _Pragma("unroll") for (int k = 0; k < 2; ++k) dst[n][k] = *(const PG8_LAS bf16x8*)(lds + PG8_SB(b, h) + boff + n * 2048 + k * 1024); } while (0)
; #define PG8_MMA(ai, bj, At, Bt) do { __builtin_amdgcn_s_setprio(1); _Pragma("unroll") for (int m = 0; m < 4; ++m) _Pragma("unroll") for (int n = 0; n < 2; ++n) _Pragma("unroll") for (int k = 0; k < 2; ++k) \
;         acc[ai][bj][m][n] = __builtin_amdgcn_mfma_f32_16x16x32_bf16(Bt[n][k], At[m][k], acc[ai][bj][m][n], 0, 0, 0); __builtin_amdgcn_s_setprio(0); } while (0)
; #define PG8_WAIT_V(n) asm volatile("s_waitcnt vmcnt(" #n ")" ::: "memory")
; #define PG8_WAIT_L(n) asm volatile("s_waitcnt lgkmcnt(" #n ")" ::: "memory")
; template <class Epi, class Sched, bool ALIGN_EPI = false, bool SP2 = false>
; __device__ __forceinline__ void gemm_phase(PG8_LAS unsigned char* lds, const Gemm g, const Sched& S, const Epi& E, int wave_in) {
;     ...
;             const bool last = (t == nt - 2);
;             const char* a1 = cA + (size_t)(t + 1) * kstep;
;             const char* a2 = last ? nA : cA + (size_t)(t + 2) * kstep; const char* b2 = last ? nB : cB + (size_t)(t + 2) * kstep;
;             const char* a3 = a2 + kstep; const char* b3 = b2 + kstep;
;             if (last && has_next) S.a_ready(nxt);
;             if constexpr (SP2) {
;             PG8_LDB(B0, 0, 0); PG8_LDB(B1, 0, 1); PG8_SCHED; PG8_LDA(At, 0, 0); PG8_STAGE(PG8_SA(1, 1), a1 + hstepA, voffA);
;             PG8_WAIT_V(8); PG8_WAIT_L(0); PG8_BAR; PG8_MMA(0, 0, At, B0); PG8_MMA(0, 1, At, B1); PG8_BAR; PG8_SCHED;
;             PG8_LDA(At, 0, 1); PG8_STAGE(PG8_SB(0, 0), b2, voffB); PG8_STAGE(PG8_SB(0, 1), b2 + hstep, voffB); PG8_STAGE(PG8_SA(0, 0), a2, voffA);
;             PG8_WAIT_V(8); PG8_WAIT_L(0); PG8_BAR; PG8_MMA(1, 0, At, B0); PG8_MMA(1, 1, At, B1); PG8_BAR; PG8_SCHED;
.LBB0_277:
	s_add_u32 s2, s0, 0xfff80080
	s_addc_u32 s3, s1, -1
	s_add_i32 s41, 0, 0x10000
	s_cmp_eq_u32 s40, 28
	s_cselect_b32 s5, s19, s3
	s_cselect_b32 s4, s36, s2
	s_cselect_b32 s3, s17, s39
	s_cselect_b32 s2, s37, s38
	s_add_i32 s44, 0, 0x14000
	v_add_u32_e32 v46, s41, v181
	v_add_u32_e32 v156, s44, v181
	ds_read_b128 v[26:29], v46
	ds_read_b128 v[30:33], v46 offset:1024
	ds_read_b128 v[42:45], v46 offset:2048
	ds_read_b128 v[46:49], v46 offset:3072
	ds_read_b128 v[168:171], v156
	ds_read_b128 v[172:175], v156 offset:1024
	ds_read_b128 v[176:179], v156 offset:2048
	ds_read_b128 v[184:187], v156 offset:3072
	s_add_i32 m0, s25, 0xc000
	ds_read_b128 v[188:191], v183
	ds_read_b128 v[212:215], v183 offset:1024
	ds_read_b128 v[216:219], v183 offset:2048
	ds_read_b128 v[220:223], v183 offset:3072
	ds_read_b128 v[224:227], v183 offset:4096
	ds_read_b128 v[228:231], v183 offset:5120
	ds_read_b128 v[232:235], v183 offset:6144
	ds_read_b128 v[236:239], v183 offset:7168
	global_load_lds_dwordx4 v152, s[0:1]
	s_add_i32 m0, s25, 0xe000
	s_nop 0
	global_load_lds_dwordx4 v154, s[0:1]
	s_waitcnt vmcnt(8)
	s_waitcnt lgkmcnt(0)
	s_barrier
	s_waitcnt lgkmcnt(0)
	v_mfma_f32_16x16x32_bf16 v[142:145], v[26:29], v[188:191], v[142:145]
	v_mfma_f32_16x16x32_bf16 v[138:141], v[42:45], v[188:191], v[138:141]
	v_mfma_f32_16x16x32_bf16 v[126:129], v[26:29], v[216:219], v[126:129]
	v_mfma_f32_16x16x32_bf16 v[122:125], v[42:45], v[216:219], v[122:125]
	v_mfma_f32_16x16x32_bf16 v[110:113], v[26:29], v[224:227], v[110:113]
	v_mfma_f32_16x16x32_bf16 v[106:109], v[42:45], v[224:227], v[106:109]
	v_mfma_f32_16x16x32_bf16 v[94:97], v[26:29], v[232:235], v[94:97]
	v_mfma_f32_16x16x32_bf16 v[90:93], v[42:45], v[232:235], v[90:93]
	v_mfma_f32_16x16x32_bf16 v[142:145], v[30:33], v[212:215], v[142:145]
	v_mfma_f32_16x16x32_bf16 v[138:141], v[46:49], v[212:215], v[138:141]
	v_mfma_f32_16x16x32_bf16 v[126:129], v[30:33], v[220:223], v[126:129]
	v_mfma_f32_16x16x32_bf16 v[122:125], v[46:49], v[220:223], v[122:125]
	v_mfma_f32_16x16x32_bf16 v[110:113], v[30:33], v[228:231], v[110:113]
	v_mfma_f32_16x16x32_bf16 v[106:109], v[46:49], v[228:231], v[106:109]
	v_mfma_f32_16x16x32_bf16 v[94:97], v[30:33], v[236:239], v[94:97]
	v_mfma_f32_16x16x32_bf16 v[90:93], v[46:49], v[236:239], v[90:93]
	v_mfma_f32_16x16x32_bf16 v[134:137], v[168:171], v[188:191], v[134:137]
	v_mfma_f32_16x16x32_bf16 v[130:133], v[176:179], v[188:191], v[130:133]
	v_mfma_f32_16x16x32_bf16 v[118:121], v[168:171], v[216:219], v[118:121]
	v_mfma_f32_16x16x32_bf16 v[114:117], v[176:179], v[216:219], v[114:117]
	v_mfma_f32_16x16x32_bf16 v[102:105], v[168:171], v[224:227], v[102:105]
	v_mfma_f32_16x16x32_bf16 v[98:101], v[176:179], v[224:227], v[98:101]
	v_mfma_f32_16x16x32_bf16 v[86:89], v[168:171], v[232:235], v[86:89]
	v_mfma_f32_16x16x32_bf16 v[82:85], v[176:179], v[232:235], v[82:85]
	v_mfma_f32_16x16x32_bf16 v[134:137], v[172:175], v[212:215], v[134:137]
	v_mfma_f32_16x16x32_bf16 v[130:133], v[184:187], v[212:215], v[130:133]
	v_mfma_f32_16x16x32_bf16 v[118:121], v[172:175], v[220:223], v[118:121]
	v_mfma_f32_16x16x32_bf16 v[114:117], v[184:187], v[220:223], v[114:117]
	v_mfma_f32_16x16x32_bf16 v[102:105], v[172:175], v[228:231], v[102:105]
	v_mfma_f32_16x16x32_bf16 v[98:101], v[184:187], v[228:231], v[98:101]
	v_mfma_f32_16x16x32_bf16 v[86:89], v[172:175], v[236:239], v[86:89]
	v_mfma_f32_16x16x32_bf16 v[82:85], v[184:187], v[236:239], v[82:85]
	s_barrier
	s_add_i32 s41, s41, s24
	s_add_u32 vcc_lo, s2, s84
	s_addc_u32 vcc_hi, s3, s85
	s_mov_b32 m0, s41
	ds_read_b128 v[188:191], v183 offset:16384
	ds_read_b128 v[212:215], v183 offset:17408
	ds_read_b128 v[216:219], v183 offset:18432
	ds_read_b128 v[220:223], v183 offset:19456
	ds_read_b128 v[224:227], v183 offset:20480
	ds_read_b128 v[228:231], v183 offset:21504
	ds_read_b128 v[232:235], v183 offset:22528
	ds_read_b128 v[236:239], v183 offset:23552
	global_load_lds_dwordx4 v0, s[2:3]
	s_add_i32 m0, s41, 0x2000
	s_add_u32 s42, s2, 0x80000
	s_addc_u32 s43, s3, 0
	s_add_i32 s41, s44, s24
	global_load_lds_dwordx4 v146, s[2:3]
	s_mov_b32 m0, s41
	s_add_u32 s98, s4, s84
	s_addc_u32 s99, s5, s85
	global_load_lds_dwordx4 v0, s[42:43]
	s_add_i32 m0, s41, 0x2000
	s_nop 0
	global_load_lds_dwordx4 v146, s[42:43]
	s_mov_b32 m0, s25
	s_nop 0
	global_load_lds_dwordx4 v150, s[4:5]
	s_mov_b32 m0, s26
	s_nop 0
	global_load_lds_dwordx4 v148, s[4:5]
	s_waitcnt vmcnt(8)
	s_waitcnt lgkmcnt(0)
	s_barrier
	s_waitcnt lgkmcnt(0)
	v_mfma_f32_16x16x32_bf16 v[78:81], v[26:29], v[188:191], v[78:81]
	v_mfma_f32_16x16x32_bf16 v[74:77], v[42:45], v[188:191], v[74:77]
	v_mfma_f32_16x16x32_bf16 v[62:65], v[26:29], v[216:219], v[62:65]
	v_mfma_f32_16x16x32_bf16 v[58:61], v[42:45], v[216:219], v[58:61]
	v_mfma_f32_16x16x32_bf16 v[38:41], v[26:29], v[224:227], v[38:41]
	v_mfma_f32_16x16x32_bf16 v[34:37], v[42:45], v[224:227], v[34:37]
	v_mfma_f32_16x16x32_bf16 v[14:17], v[26:29], v[232:235], v[14:17]
	v_mfma_f32_16x16x32_bf16 v[10:13], v[42:45], v[232:235], v[10:13]
	v_mfma_f32_16x16x32_bf16 v[78:81], v[30:33], v[212:215], v[78:81]
	v_mfma_f32_16x16x32_bf16 v[74:77], v[46:49], v[212:215], v[74:77]
	v_mfma_f32_16x16x32_bf16 v[62:65], v[30:33], v[220:223], v[62:65]
	v_mfma_f32_16x16x32_bf16 v[58:61], v[46:49], v[220:223], v[58:61]
	v_mfma_f32_16x16x32_bf16 v[38:41], v[30:33], v[228:231], v[38:41]
	v_mfma_f32_16x16x32_bf16 v[34:37], v[46:49], v[228:231], v[34:37]
	v_mfma_f32_16x16x32_bf16 v[14:17], v[30:33], v[236:239], v[14:17]
	v_mfma_f32_16x16x32_bf16 v[10:13], v[46:49], v[236:239], v[10:13]
	v_mfma_f32_16x16x32_bf16 v[22:25], v[168:171], v[224:227], v[22:25]
	v_mfma_f32_16x16x32_bf16 v[18:21], v[176:179], v[224:227], v[18:21]
	v_mfma_f32_16x16x32_bf16 v[6:9], v[168:171], v[232:235], v[6:9]
	v_mfma_f32_16x16x32_bf16 v[2:5], v[176:179], v[232:235], v[2:5]
	v_mfma_f32_16x16x32_bf16 v[26:29], v[168:171], v[188:191], v[70:73]
	v_mfma_f32_16x16x32_bf16 v[30:33], v[176:179], v[188:191], v[66:69]
	v_mfma_f32_16x16x32_bf16 v[42:45], v[168:171], v[216:219], v[54:57]
	v_mfma_f32_16x16x32_bf16 v[46:49], v[176:179], v[216:219], v[50:53]
	v_mfma_f32_16x16x32_bf16 v[22:25], v[172:175], v[228:231], v[22:25]
	v_mfma_f32_16x16x32_bf16 v[18:21], v[184:187], v[228:231], v[18:21]
	v_mfma_f32_16x16x32_bf16 v[6:9], v[172:175], v[236:239], v[6:9]
	v_mfma_f32_16x16x32_bf16 v[2:5], v[184:187], v[236:239], v[2:5]
	v_mfma_f32_16x16x32_bf16 v[26:29], v[172:175], v[212:215], v[26:29]
	v_mfma_f32_16x16x32_bf16 v[30:33], v[184:187], v[212:215], v[30:33]
	v_mfma_f32_16x16x32_bf16 v[42:45], v[172:175], v[220:223], v[42:45]
	v_mfma_f32_16x16x32_bf16 v[46:49], v[184:187], v[220:223], v[46:49]
	s_barrier
; #define PG8_STAGE(bufoff, gbase, voff) do { _Pragma("unroll") for (int _i = 0; _i < 2; ++_i) \
;         __builtin_amdgcn_global_load_lds((const unsigned*)((const char*)(gbase) + (voff)[_i]), (PG8_LAS unsigned*)(lds + (bufoff) + ldsw + _i * 8192), 16, 0, 0); } while (0)
; #define PG8_LDA(dst, b, h) do { _Pragma("unroll") for (int m = 0; m < 4; ++m) _Pragma("unroll") for (int k = 0; k < 2; ++k) dst[m][k] = *(const PG8_LAS bf16x8*)(lds + PG8_SA(b, h) + aoff + m * 2048 + k * 1024); } while (0)
; #define PG8_LDB(dst, b, h) do { _Pragma("unroll") for (int n = 0; n < 2; ++n) _Pragma("unroll") for (int k = 0; k < 2; ++k) dst[n][k] = *(const PG8_LAS bf16x8*)(lds + PG8_SB(b, h) + boff + n * 2048 + k * 1024); } while (0)
; #define PG8_MMA(ai, bj, At, Bt) do { __builtin_amdgcn_s_setprio(1); _Pragma("unroll") for (int m = 0; m < 4; ++m) _Pragma("unroll") for (int n = 0; n < 2; ++n) _Pragma("unroll") for (int k = 0; k < 2; ++k) \
;         acc[ai][bj][m][n] = __builtin_amdgcn_mfma_f32_16x16x32_bf16(Bt[n][k], At[m][k], acc[ai][bj][m][n], 0, 0, 0); __builtin_amdgcn_s_setprio(0); } while (0)
; #define PG8_WAIT_V(n) asm volatile("s_waitcnt vmcnt(" #n ")" ::: "memory")
; #define PG8_WAIT_L(n) asm volatile("s_waitcnt lgkmcnt(" #n ")" ::: "memory")
; #define PG8_BAR __builtin_amdgcn_s_barrier()
; #define PG8_SCHED __builtin_amdgcn_sched_barrier(0)
; template <class Epi, class Sched, bool ALIGN_EPI = false, bool SP2 = false>
; __device__ __forceinline__ void gemm_phase(PG8_LAS unsigned char* lds, const Gemm g, const Sched& S, const Epi& E, int wave_in) {
;     ...
;             PG8_LDB(B0, 1, 0); PG8_LDB(B1, 1, 1); PG8_SCHED; PG8_LDA(At, 1, 0); PG8_STAGE(PG8_SA(0, 1), a2 + hstepA, voffA);
;             PG8_WAIT_V(8); PG8_WAIT_L(0); PG8_BAR; PG8_MMA(0, 0, At, B0); PG8_MMA(0, 1, At, B1); PG8_BAR; PG8_SCHED;
;             PG8_LDA(At, 1, 1); PG8_STAGE(PG8_SB(1, 0), b3, voffB); PG8_STAGE(PG8_SB(1, 1), b3 + hstep, voffB); PG8_STAGE(PG8_SA(1, 0), a3, voffA);
;             PG8_WAIT_V(8); PG8_WAIT_L(0); PG8_BAR; PG8_MMA(1, 0, At, B0); PG8_MMA(1, 1, At, B1); PG8_BAR; PG8_SCHED;
	s_add_i32 s41, 0, 0x18000
	s_add_i32 s42, 0, 0x1c000
	v_add_u32_e32 v70, s41, v181
	v_add_u32_e32 v184, s42, v181
	ds_read_b128 v[50:53], v70
	ds_read_b128 v[54:57], v70 offset:1024
	ds_read_b128 v[66:69], v70 offset:2048
	ds_read_b128 v[70:73], v70 offset:3072
	ds_read_b128 v[168:171], v184
	ds_read_b128 v[172:175], v184 offset:1024
	ds_read_b128 v[176:179], v184 offset:2048
	ds_read_b128 v[184:187], v184 offset:3072
	s_add_u32 s4, s4, 0x80000
	s_addc_u32 s5, s5, 0
	s_mov_b32 m0, s27
	ds_read_b128 v[188:191], v183 offset:32768
	ds_read_b128 v[212:215], v183 offset:33792
	ds_read_b128 v[216:219], v183 offset:34816
	ds_read_b128 v[220:223], v183 offset:35840
	ds_read_b128 v[224:227], v183 offset:36864
	ds_read_b128 v[228:231], v183 offset:37888
	ds_read_b128 v[232:235], v183 offset:38912
	ds_read_b128 v[236:239], v183 offset:39936
	global_load_lds_dwordx4 v150, s[4:5]
	s_mov_b32 m0, s28
	s_nop 0
	global_load_lds_dwordx4 v148, s[4:5]
	s_waitcnt vmcnt(8)
	s_waitcnt lgkmcnt(0)
	s_barrier
	s_waitcnt lgkmcnt(0)
	v_mfma_f32_16x16x32_bf16 v[142:145], v[50:53], v[188:191], v[142:145]
	v_mfma_f32_16x16x32_bf16 v[138:141], v[66:69], v[188:191], v[138:141]
	v_mfma_f32_16x16x32_bf16 v[126:129], v[50:53], v[216:219], v[126:129]
	v_mfma_f32_16x16x32_bf16 v[122:125], v[66:69], v[216:219], v[122:125]
	v_mfma_f32_16x16x32_bf16 v[110:113], v[50:53], v[224:227], v[110:113]
	v_mfma_f32_16x16x32_bf16 v[106:109], v[66:69], v[224:227], v[106:109]
	v_mfma_f32_16x16x32_bf16 v[94:97], v[50:53], v[232:235], v[94:97]
	v_mfma_f32_16x16x32_bf16 v[90:93], v[66:69], v[232:235], v[90:93]
	v_mfma_f32_16x16x32_bf16 v[142:145], v[54:57], v[212:215], v[142:145]
	v_mfma_f32_16x16x32_bf16 v[138:141], v[70:73], v[212:215], v[138:141]
	v_mfma_f32_16x16x32_bf16 v[126:129], v[54:57], v[220:223], v[126:129]
	v_mfma_f32_16x16x32_bf16 v[122:125], v[70:73], v[220:223], v[122:125]
	v_mfma_f32_16x16x32_bf16 v[110:113], v[54:57], v[228:231], v[110:113]
	v_mfma_f32_16x16x32_bf16 v[106:109], v[70:73], v[228:231], v[106:109]
	v_mfma_f32_16x16x32_bf16 v[94:97], v[54:57], v[236:239], v[94:97]
	v_mfma_f32_16x16x32_bf16 v[90:93], v[70:73], v[236:239], v[90:93]
	v_mfma_f32_16x16x32_bf16 v[134:137], v[168:171], v[188:191], v[134:137]
	v_mfma_f32_16x16x32_bf16 v[130:133], v[176:179], v[188:191], v[130:133]
	v_mfma_f32_16x16x32_bf16 v[118:121], v[168:171], v[216:219], v[118:121]
	v_mfma_f32_16x16x32_bf16 v[114:117], v[176:179], v[216:219], v[114:117]
	v_mfma_f32_16x16x32_bf16 v[102:105], v[168:171], v[224:227], v[102:105]
	v_mfma_f32_16x16x32_bf16 v[98:101], v[176:179], v[224:227], v[98:101]
	v_mfma_f32_16x16x32_bf16 v[86:89], v[168:171], v[232:235], v[86:89]
	v_mfma_f32_16x16x32_bf16 v[82:85], v[176:179], v[232:235], v[82:85]
	v_mfma_f32_16x16x32_bf16 v[134:137], v[172:175], v[212:215], v[134:137]
	v_mfma_f32_16x16x32_bf16 v[130:133], v[184:187], v[212:215], v[130:133]
	v_mfma_f32_16x16x32_bf16 v[118:121], v[172:175], v[220:223], v[118:121]
	v_mfma_f32_16x16x32_bf16 v[114:117], v[184:187], v[220:223], v[114:117]
	v_mfma_f32_16x16x32_bf16 v[102:105], v[172:175], v[228:231], v[102:105]
	v_mfma_f32_16x16x32_bf16 v[98:101], v[184:187], v[228:231], v[98:101]
	v_mfma_f32_16x16x32_bf16 v[86:89], v[172:175], v[236:239], v[86:89]
	v_mfma_f32_16x16x32_bf16 v[82:85], v[184:187], v[236:239], v[82:85]
	s_barrier
	s_add_i32 s4, s41, s24
	s_mov_b32 m0, s4
	ds_read_b128 v[188:191], v183 offset:49152
	ds_read_b128 v[212:215], v183 offset:50176
	ds_read_b128 v[216:219], v183 offset:51200
	ds_read_b128 v[220:223], v183 offset:52224
	ds_read_b128 v[224:227], v183 offset:53248
	ds_read_b128 v[228:231], v183 offset:54272
	ds_read_b128 v[232:235], v183 offset:55296
	ds_read_b128 v[236:239], v183 offset:56320
	global_load_lds_dwordx4 v0, vcc
	s_add_i32 m0, s4, 0x2000
	s_add_u32 s2, s2, 0x80080
	s_addc_u32 s3, s3, 0
	s_add_i32 s4, s42, s24
	global_load_lds_dwordx4 v146, vcc
	s_mov_b32 m0, s4
	s_nop 0
	global_load_lds_dwordx4 v0, s[2:3]
	s_add_i32 m0, s4, 0x2000
	s_nop 0
	global_load_lds_dwordx4 v146, s[2:3]
	s_mov_b32 m0, s29
	s_nop 0
	global_load_lds_dwordx4 v150, s[98:99]
	s_mov_b32 m0, s30
	s_nop 0
	global_load_lds_dwordx4 v148, s[98:99]
	s_waitcnt vmcnt(8)
	s_waitcnt lgkmcnt(0)
	s_barrier
	s_waitcnt lgkmcnt(0)
	v_mfma_f32_16x16x32_bf16 v[78:81], v[50:53], v[188:191], v[78:81]
	v_mfma_f32_16x16x32_bf16 v[74:77], v[66:69], v[188:191], v[74:77]
	v_mfma_f32_16x16x32_bf16 v[62:65], v[50:53], v[216:219], v[62:65]
	v_mfma_f32_16x16x32_bf16 v[58:61], v[66:69], v[216:219], v[58:61]
	v_mfma_f32_16x16x32_bf16 v[38:41], v[50:53], v[224:227], v[38:41]
	v_mfma_f32_16x16x32_bf16 v[34:37], v[66:69], v[224:227], v[34:37]
	v_mfma_f32_16x16x32_bf16 v[14:17], v[50:53], v[232:235], v[14:17]
	v_mfma_f32_16x16x32_bf16 v[10:13], v[66:69], v[232:235], v[10:13]
	v_mfma_f32_16x16x32_bf16 v[78:81], v[54:57], v[212:215], v[78:81]
	v_mfma_f32_16x16x32_bf16 v[74:77], v[70:73], v[212:215], v[74:77]
	v_mfma_f32_16x16x32_bf16 v[62:65], v[54:57], v[220:223], v[62:65]
	v_mfma_f32_16x16x32_bf16 v[58:61], v[70:73], v[220:223], v[58:61]
	v_mfma_f32_16x16x32_bf16 v[38:41], v[54:57], v[228:231], v[38:41]
	v_mfma_f32_16x16x32_bf16 v[34:37], v[70:73], v[228:231], v[34:37]
	v_mfma_f32_16x16x32_bf16 v[14:17], v[54:57], v[236:239], v[14:17]
	v_mfma_f32_16x16x32_bf16 v[10:13], v[70:73], v[236:239], v[10:13]
	v_mfma_f32_16x16x32_bf16 v[26:29], v[168:171], v[188:191], v[26:29]
	v_mfma_f32_16x16x32_bf16 v[70:73], v[172:175], v[212:215], v[26:29]
	v_mfma_f32_16x16x32_bf16 v[26:29], v[176:179], v[188:191], v[30:33]
	v_mfma_f32_16x16x32_bf16 v[66:69], v[184:187], v[212:215], v[26:29]
	v_mfma_f32_16x16x32_bf16 v[26:29], v[168:171], v[216:219], v[42:45]
	v_mfma_f32_16x16x32_bf16 v[54:57], v[172:175], v[220:223], v[26:29]
	v_mfma_f32_16x16x32_bf16 v[26:29], v[176:179], v[216:219], v[46:49]
	v_mfma_f32_16x16x32_bf16 v[22:25], v[168:171], v[224:227], v[22:25]
	v_mfma_f32_16x16x32_bf16 v[18:21], v[176:179], v[224:227], v[18:21]
	v_mfma_f32_16x16x32_bf16 v[6:9], v[168:171], v[232:235], v[6:9]
	v_mfma_f32_16x16x32_bf16 v[2:5], v[176:179], v[232:235], v[2:5]
	v_mfma_f32_16x16x32_bf16 v[50:53], v[184:187], v[220:223], v[26:29]
	v_mfma_f32_16x16x32_bf16 v[22:25], v[172:175], v[228:231], v[22:25]
	v_mfma_f32_16x16x32_bf16 v[18:21], v[184:187], v[228:231], v[18:21]
	v_mfma_f32_16x16x32_bf16 v[6:9], v[172:175], v[236:239], v[6:9]
	v_mfma_f32_16x16x32_bf16 v[2:5], v[184:187], v[236:239], v[2:5]
	s_barrier
	s_add_i32 s40, s40, 2
	s_add_u32 s0, s0, 0x100
	s_addc_u32 s1, s1, 0
	s_add_u32 s38, s38, 0x100
	s_addc_u32 s39, s39, 0
	s_cmp_gt_u32 s40, 29
	s_cbranch_scc0 .LBB0_277
	s_and_b64 vcc, exec, s[14:15]
	s_cbranch_vccz .LBB0_280
	s_barrier

; template <class Epi, class Sched, bool ALIGN_EPI = false, bool SP2 = false>
; __device__ __forceinline__ void gemm_phase(PG8_LAS unsigned char* lds, const Gemm g, const Sched& S, const Epi& E, int wave_in) {
;     ...
; #pragma unroll
;         for (int a = 0; a < 2; ++a)
; #pragma unroll
;             for (int b = 0; b < 2; ++b)
; #pragma unroll
;                 for (int m = 0; m < 4; ++m)
; #pragma unroll
;                     for (int n = 0; n < 2; ++n) acc[a][b][m][n] = (f32x4){0.f, 0.f, 0.f, 0.f};
;         cur = nxt; cA = nA; cB = nB; ++ui;
.LBB0_403:
	s_add_u32 s4, s24, 0x80
	s_addc_u32 s5, s25, 0
	s_add_u32 s24, s6, 0x100
	v_mov_b32_e32 v2, 0
	s_addc_u32 s25, s7, 0
	s_mov_b32 s6, 0
	v_mov_b32_e32 v3, v2
	v_mov_b32_e32 v4, v2
	v_mov_b32_e32 v5, v2
	v_mov_b32_e32 v6, v2
	s_waitcnt lgkmcnt(0)
	v_mov_b32_e32 v7, v2
	v_mov_b32_e32 v8, v2
	v_mov_b32_e32 v9, v2
	v_mov_b32_e32 v18, v2
	v_mov_b32_e32 v19, v2
	v_mov_b32_e32 v20, v2
	v_mov_b32_e32 v21, v2
	v_mov_b32_e32 v22, v2
	v_mov_b32_e32 v23, v2
	s_waitcnt vmcnt(0)
	v_mov_b32_e32 v24, v2
	v_mov_b32_e32 v25, v2
	v_mov_b32_e32 v34, v2
	v_mov_b32_e32 v35, v2
	v_mov_b32_e32 v36, v2
	v_mov_b32_e32 v37, v2
	v_mov_b32_e32 v38, v2
	v_mov_b32_e32 v39, v2
	v_mov_b32_e32 v40, v2
	v_mov_b32_e32 v41, v2
	v_mov_b32_e32 v50, v2
	v_mov_b32_e32 v51, v2
	v_mov_b32_e32 v52, v2
	v_mov_b32_e32 v53, v2
	v_mov_b32_e32 v54, v2
	v_mov_b32_e32 v55, v2
	v_mov_b32_e32 v56, v2
	v_mov_b32_e32 v57, v2
	v_mov_b32_e32 v10, v2
	v_mov_b32_e32 v11, v2
	v_mov_b32_e32 v12, v2
	v_mov_b32_e32 v13, v2
	v_mov_b32_e32 v14, v2
	v_mov_b32_e32 v15, v2
	v_mov_b32_e32 v16, v2
	v_mov_b32_e32 v17, v2
	v_mov_b32_e32 v26, v2
	v_mov_b32_e32 v27, v2
	v_mov_b32_e32 v28, v2
	v_mov_b32_e32 v29, v2
	v_mov_b32_e32 v30, v2
	v_mov_b32_e32 v31, v2
	v_mov_b32_e32 v32, v2
	v_mov_b32_e32 v33, v2
	v_mov_b32_e32 v42, v2
	v_mov_b32_e32 v43, v2
	v_mov_b32_e32 v44, v2
	v_mov_b32_e32 v45, v2
	v_mov_b32_e32 v46, v2
	v_mov_b32_e32 v47, v2
	v_mov_b32_e32 v48, v2
	v_mov_b32_e32 v49, v2
	v_mov_b32_e32 v58, v2
	v_mov_b32_e32 v59, v2
	v_mov_b32_e32 v60, v2
	v_mov_b32_e32 v61, v2
	v_mov_b32_e32 v62, v2
	v_mov_b32_e32 v63, v2
	v_mov_b32_e32 v64, v2
	v_mov_b32_e32 v65, v2
	v_mov_b32_e32 v66, v2
	v_mov_b32_e32 v67, v2
	v_mov_b32_e32 v68, v2
	v_mov_b32_e32 v69, v2
	v_mov_b32_e32 v70, v2
	v_mov_b32_e32 v71, v2
	v_mov_b32_e32 v72, v2
	v_mov_b32_e32 v73, v2
	v_mov_b32_e32 v82, v2
	v_mov_b32_e32 v83, v2
	v_mov_b32_e32 v84, v2
	v_mov_b32_e32 v85, v2
	v_mov_b32_e32 v86, v2
	v_mov_b32_e32 v87, v2
	v_mov_b32_e32 v88, v2
	v_mov_b32_e32 v89, v2
	v_mov_b32_e32 v98, v2
	v_mov_b32_e32 v99, v2
	v_mov_b32_e32 v100, v2
	v_mov_b32_e32 v101, v2
	v_mov_b32_e32 v102, v2
	v_mov_b32_e32 v103, v2
	v_mov_b32_e32 v104, v2
	v_mov_b32_e32 v105, v2
	v_mov_b32_e32 v114, v2
	v_mov_b32_e32 v115, v2
	v_mov_b32_e32 v116, v2
	v_mov_b32_e32 v117, v2
	v_mov_b32_e32 v118, v2
	v_mov_b32_e32 v119, v2
	v_mov_b32_e32 v120, v2
	v_mov_b32_e32 v121, v2
	v_mov_b32_e32 v74, v2
	v_mov_b32_e32 v75, v2
	v_mov_b32_e32 v76, v2
	v_mov_b32_e32 v77, v2
	v_mov_b32_e32 v78, v2
	v_mov_b32_e32 v79, v2
	v_mov_b32_e32 v80, v2
	v_mov_b32_e32 v81, v2
	v_mov_b32_e32 v90, v2
	v_mov_b32_e32 v91, v2
	v_mov_b32_e32 v92, v2
	v_mov_b32_e32 v93, v2
	v_mov_b32_e32 v94, v2
	v_mov_b32_e32 v95, v2
	v_mov_b32_e32 v96, v2
	v_mov_b32_e32 v97, v2
	v_mov_b32_e32 v106, v2
	v_mov_b32_e32 v107, v2
	v_mov_b32_e32 v108, v2
	v_mov_b32_e32 v109, v2
	v_mov_b32_e32 v110, v2
	v_mov_b32_e32 v111, v2
	v_mov_b32_e32 v112, v2
	v_mov_b32_e32 v113, v2
	v_mov_b32_e32 v122, v2
	v_mov_b32_e32 v123, v2
	v_mov_b32_e32 v124, v2
	v_mov_b32_e32 v125, v2
	v_mov_b32_e32 v126, v2
	v_mov_b32_e32 v127, v2
	v_mov_b32_e32 v128, v2
	v_mov_b32_e32 v129, v2
	s_nop 0
	s_nop 0
	s_nop 0
	s_nop 0
	s_nop 0
.LBB0_404:
	s_cmp_eq_u32 s100, 1
	s_cbranch_scc0 .Lmg_nohook
	s_cmp_eq_u32 s6, 16
	s_cbranch_scc1 .Lmg_rescale01
	s_cmp_eq_u32 s6, 24
	s_cbranch_scc1 .Lmg_rescale12
